# P13 final norm: hoist loop-invariant g_final loads out of the row loop, removes 8 vmcnt(0) drains per iteration between output stores
# baseline (speedup 1.0000x reference)
; __global__ void __launch_bounds__(NWAVES * 64, 2) fwd(Args args) {
;     ...
;         const f32x4* gfp = (const f32x4*)g_final + 2 * F.lane;
;         for (int row = gw; row < T; row += 2 * NGW) {
;             const int row2 = row + NGW;
;             const float pa = part[(size_t)row * 64 + F.lane], pb = part[(size_t)row2 * 64 + F.lane];
;             const u32x4* hp = (const u32x4*)(hb + (size_t)row * DM) + F.lane; const u32x4* hq = (const u32x4*)(hb + (size_t)row2 * DM) + F.lane; u32x4 wa[8], wb[8];
; #pragma unroll
;             for (int j = 0; j < 8; ++j) { wa[j] = hp[64 * j]; wb[j] = hq[64 * j]; }
;             const float rsa = 1.0f / sqrtf(wave_sum(pa) * (1.0f / DM) + EPS), rsb = 1.0f / sqrtf(wave_sum(pb) * (1.0f / DM) + EPS);
;             f32x4* oa = (f32x4*)(F.out + (size_t)row * DM) + 2 * F.lane; f32x4* ob = (f32x4*)(F.out + (size_t)row2 * DM) + 2 * F.lane;
.LBB0_1711:
	s_cmp_lt_i32 s96, 14
	s_cselect_b64 s[2:3], -1, 0
	s_and_b64 s[0:1], s[2:3], s[0:1]
	s_andn2_b64 vcc, exec, s[0:1]
	s_cbranch_vccnz .LBB0_1715
	s_waitcnt lgkmcnt(0)
	v_mov_b64_e32 v[0:1], s[92:93]
	flat_load_dwordx2 v[0:1], v[0:1] offset:136 sc0 sc1
	s_waitcnt vmcnt(0)
	s_cmpk_gt_i32 s82, 0x3fff
	s_cbranch_scc1 .LBB0_1715
	v_lshlrev_b32_e32 v40, 5, v182
	v_mov_b32_e32 v41, 0
	s_waitcnt lgkmcnt(0)
	v_lshl_add_u64 v[42:43], v[0:1], 0, v[40:41]
	v_mbcnt_lo_u32_b32 v0, -1, 0
	v_mbcnt_hi_u32_b32 v0, -1, v0
	v_and_b32_e32 v1, 64, v0
	v_add_u32_e32 v1, 64, v1
	v_xor_b32_e32 v2, 1, v0
	v_cmp_lt_i32_e32 vcc, v2, v1
	s_mov_b64 s[0:1], 0x1000
	v_lshl_add_u64 v[44:45], v[42:43], 0, s[0:1]
	v_cndmask_b32_e32 v2, v0, v2, vcc
	v_lshlrev_b32_e32 v90, 2, v2
	v_xor_b32_e32 v2, 2, v0
	v_cmp_lt_i32_e32 vcc, v2, v1
	s_mov_b64 s[0:1], 0x1010
	v_lshl_add_u64 v[46:47], v[42:43], 0, s[0:1]
	v_cndmask_b32_e32 v2, v0, v2, vcc
	v_lshlrev_b32_e32 v91, 2, v2
	v_xor_b32_e32 v2, 4, v0
	v_cmp_lt_i32_e32 vcc, v2, v1
	s_mov_b64 s[0:1], 0x1800
	v_lshl_add_u64 v[48:49], v[42:43], 0, s[0:1]
	v_cndmask_b32_e32 v2, v0, v2, vcc
	s_mov_b64 s[0:1], 0x1810
	v_lshlrev_b32_e32 v92, 2, v2
	v_xor_b32_e32 v2, 8, v0
	v_lshl_add_u64 v[50:51], v[42:43], 0, s[0:1]
	s_mov_b64 s[0:1], 0x2000
	v_cmp_lt_i32_e32 vcc, v2, v1
	v_lshl_add_u64 v[52:53], v[42:43], 0, s[0:1]
	s_mov_b64 s[0:1], 0x2010
	v_cndmask_b32_e32 v2, v0, v2, vcc
	v_lshl_add_u64 v[54:55], v[42:43], 0, s[0:1]
	s_mov_b64 s[0:1], 0x2800
	v_lshlrev_b32_e32 v93, 2, v2
	v_xor_b32_e32 v2, 16, v0
	v_lshl_add_u64 v[56:57], v[42:43], 0, s[0:1]
	s_mov_b64 s[0:1], 0x2810
	v_cmp_lt_i32_e32 vcc, v2, v1
	v_lshl_add_u64 v[58:59], v[42:43], 0, s[0:1]
	s_mov_b64 s[0:1], 0x3000
	v_cndmask_b32_e32 v2, v0, v2, vcc
	v_lshl_add_u64 v[60:61], v[42:43], 0, s[0:1]
	s_mov_b64 s[0:1], 0x3010
	v_lshlrev_b32_e32 v94, 2, v2
	v_xor_b32_e32 v2, 32, v0
	v_lshl_add_u64 v[62:63], v[42:43], 0, s[0:1]
	s_mov_b64 s[0:1], 0x3800
	v_cmp_lt_i32_e32 vcc, v2, v1
	s_lshl_b32 s6, s88, 4
	v_lshl_add_u64 v[64:65], v[42:43], 0, s[0:1]
	s_mov_b64 s[0:1], 0x3810
	s_ashr_i32 s83, s82, 31
	v_cndmask_b32_e32 v0, v0, v2, vcc
	v_lshl_add_u64 v[66:67], v[42:43], 0, s[0:1]
	s_lshl_b64 s[0:1], s[82:83], 13
	v_lshlrev_b32_e32 v2, 4, v182
	s_ashr_i32 s7, s6, 31
	v_or_b32_e32 v68, s0, v2
	v_mov_b32_e32 v69, s1
	s_lshl_b64 s[8:9], s[6:7], 13
	s_lshl_b64 s[0:1], s[82:83], 14
	s_add_u32 s10, s76, s0
	s_addc_u32 s11, s77, s1
	s_add_i32 s0, s82, s68
	s_ashr_i32 s1, s0, 31
	s_lshl_b64 s[12:13], s[6:7], 14
	s_lshl_b64 s[2:3], s[0:1], 8
	s_lshl_b64 s[14:15], s[6:7], 8
	s_lshl_b64 s[4:5], s[0:1], 14
	v_lshlrev_b32_e32 v3, 2, v182
	s_add_u32 s16, s76, s4
	v_lshlrev_b32_e32 v95, 2, v0
	v_or_b32_e32 v0, s2, v3
	v_mov_b32_e32 v1, s3
	s_mov_b64 s[2:3], 0x400000
	s_addc_u32 s17, s77, s5
	s_lshl_b64 s[4:5], s[82:83], 8
	v_lshl_add_u64 v[70:71], v[0:1], 0, s[2:3]
	v_or_b32_e32 v0, s4, v3
	v_mov_b32_e32 v1, s5
	s_lshl_b64 s[0:1], s[0:1], 13
	v_lshl_add_u64 v[72:73], v[0:1], 0, s[2:3]
	v_or_b32_e32 v74, s0, v2
	v_mov_b32_e32 v75, s1
	s_mov_b32 s7, 0x26001000
	v_mov_b32_e32 v96, 0x358637bd
	s_mov_b32 s18, 0xf800000
	v_mov_b32_e32 v97, 0x260
	s_movk_i32 s19, 0x1000
	s_movk_i32 s20, 0x2000
	s_movk_i32 s21, 0x3000
	global_load_dwordx4 v[184:187], v[42:43], off
	global_load_dwordx4 v[188:191], v[42:43], off offset:16
	global_load_dwordx4 v[192:195], v[42:43], off offset:2048
	global_load_dwordx4 v[196:199], v[42:43], off offset:2064
	global_load_dwordx4 v[200:203], v[44:45], off
	global_load_dwordx4 v[204:207], v[46:47], off
	global_load_dwordx4 v[208:211], v[48:49], off
	global_load_dwordx4 v[212:215], v[50:51], off
	global_load_dwordx4 v[216:219], v[52:53], off
	global_load_dwordx4 v[220:223], v[54:55], off
	global_load_dwordx4 v[224:227], v[56:57], off
	global_load_dwordx4 v[228:231], v[58:59], off
	global_load_dwordx4 v[232:235], v[60:61], off
	global_load_dwordx4 v[236:239], v[62:63], off
	global_load_dwordx4 v[240:243], v[64:65], off
	global_load_dwordx4 v[244:247], v[66:67], off
	s_waitcnt vmcnt(0)
.LBB0_1714:
	v_lshl_add_u64 v[4:5], s[78:79], 0, v[72:73]
	v_lshl_add_u64 v[6:7], s[78:79], 0, v[70:71]
	v_lshl_add_u64 v[2:3], s[78:79], 0, v[68:69]
	global_load_dword v163, v[4:5], off
	global_load_dword v164, v[6:7], off
	v_add_co_u32_e32 v4, vcc, 0x26000000, v2
	v_lshl_add_u64 v[0:1], s[78:79], 0, v[74:75]
	s_nop 0
	v_addc_co_u32_e32 v5, vcc, 0, v3, vcc
	global_load_dwordx4 v[98:101], v[4:5], off
	global_load_dwordx4 v[102:105], v[4:5], off offset:1024
	global_load_dwordx4 v[106:109], v[4:5], off offset:2048
	v_add_co_u32_e32 v6, vcc, 0x26000000, v0
	v_lshl_add_u64 v[78:79], s[10:11], 0, v[40:41]
	s_nop 0
	v_addc_co_u32_e32 v7, vcc, 0, v1, vcc
	global_load_dwordx4 v[110:113], v[6:7], off
	global_load_dwordx4 v[114:117], v[6:7], off offset:1024
	global_load_dwordx4 v[118:121], v[6:7], off offset:2048
	global_load_dwordx4 v[122:125], v[4:5], off offset:3072
	global_load_dwordx4 v[126:129], v[6:7], off offset:3072
	v_add_co_u32_e64 v84, s[0:1], s19, v78
	v_lshl_add_u64 v[76:77], s[16:17], 0, v[40:41]
	s_nop 0
	v_addc_co_u32_e64 v85, s[0:1], 0, v79, s[0:1]
	v_add_co_u32_e64 v80, s[0:1], s20, v78
	v_add_co_u32_e32 v2, vcc, s7, v2
	s_nop 0
	v_addc_co_u32_e64 v81, s[0:1], 0, v79, s[0:1]
	v_add_co_u32_e64 v86, s[0:1], s19, v76
	v_addc_co_u32_e32 v3, vcc, 0, v3, vcc
	s_nop 0
	v_addc_co_u32_e64 v87, s[0:1], 0, v77, s[0:1]
	v_add_co_u32_e64 v82, s[0:1], s20, v76
	v_add_co_u32_e32 v0, vcc, s7, v0
	s_nop 0
	v_addc_co_u32_e64 v83, s[0:1], 0, v77, s[0:1]
	v_addc_co_u32_e32 v1, vcc, 0, v1, vcc
	global_load_dwordx4 v[36:39], v[2:3], off
	global_load_dwordx4 v[20:23], v[2:3], off offset:1024
	global_load_dwordx4 v[12:15], v[2:3], off offset:2048
	global_load_dwordx4 v[16:19], v[0:1], off offset:1024
	global_load_dwordx4 v[8:11], v[0:1], off offset:2048
	global_load_dwordx4 v[32:35], v[0:1], off
	global_load_dwordx4 v[4:7], v[2:3], off offset:3072
	s_nop 0
	global_load_dwordx4 v[0:3], v[0:1], off offset:3072
	s_add_i32 s82, s82, s6
	s_add_u32 s10, s10, s12
	s_addc_u32 s11, s11, s13
	s_add_u32 s16, s16, s12
	s_addc_u32 s17, s17, s13
	v_lshl_add_u64 v[68:69], v[68:69], 0, s[8:9]
	v_lshl_add_u64 v[70:71], v[70:71], 0, s[14:15]
	v_lshl_add_u64 v[72:73], v[72:73], 0, s[14:15]
	v_lshl_add_u64 v[74:75], v[74:75], 0, s[8:9]
	s_cmpk_lt_i32 s82, 0x4000
	s_waitcnt vmcnt(0)
; __device__ __forceinline__ float bflo(unsigned w) { return __uint_as_float(w << 16); }
; __device__ __forceinline__ float bfhi(unsigned w) { return __uint_as_float(w & 0xffff0000u); }
; __global__ void __launch_bounds__(NWAVES * 64, 2) fwd(Args args) {
;     ...
;             const float rsa = 1.0f / sqrtf(wave_sum(pa) * (1.0f / DM) + EPS), rsb = 1.0f / sqrtf(wave_sum(pb) * (1.0f / DM) + EPS);
;             f32x4* oa = (f32x4*)(F.out + (size_t)row * DM) + 2 * F.lane; f32x4* ob = (f32x4*)(F.out + (size_t)row2 * DM) + 2 * F.lane;
; #pragma unroll
;             for (int j = 0; j < 8; ++j) { const f32x4 g0 = gfp[128 * j], g1 = gfp[128 * j + 1]; const u32x4 w = wa[j], w2 = wb[j];
;                 const f32x4 v0 = {bflo(w.x) * g0[0] * rsa, bfhi(w.x) * g0[1] * rsa, bflo(w.y) * g0[2] * rsa, bfhi(w.y) * g0[3] * rsa}, v1 = {bflo(w.z) * g1[0] * rsa, bfhi(w.z) * g1[1] * rsa, bflo(w.w) * g1[2] * rsa, bfhi(w.w) * g1[3] * rsa};
;                 const f32x4 u0 = {bflo(w2.x) * g0[0] * rsb, bfhi(w2.x) * g0[1] * rsb, bflo(w2.y) * g0[2] * rsb, bfhi(w2.y) * g0[3] * rsb}, u1 = {bflo(w2.z) * g1[0] * rsb, bfhi(w2.z) * g1[1] * rsb, bflo(w2.w) * g1[2] * rsb, bfhi(w2.w) * g1[3] * rsb};
;                 __builtin_nontemporal_store(v0, oa + 128 * j); __builtin_nontemporal_store(v1, oa + 128 * j + 1); __builtin_nontemporal_store(u0, ob + 128 * j); __builtin_nontemporal_store(u1, ob + 128 * j + 1); } }
	ds_bpermute_b32 v165, v90, v163
	ds_bpermute_b32 v166, v90, v164
	v_lshlrev_b32_e32 v132, 16, v100
	v_and_b32_e32 v133, 0xffff0000, v100
	v_lshlrev_b32_e32 v88, 16, v106
	v_and_b32_e32 v89, 0xffff0000, v106
	v_lshlrev_b32_e32 v142, 16, v107
	v_and_b32_e32 v143, 0xffff0000, v107
	v_lshlrev_b32_e32 v144, 16, v108
	v_and_b32_e32 v145, 0xffff0000, v108
	v_lshlrev_b32_e32 v146, 16, v109
	v_and_b32_e32 v147, 0xffff0000, v109
	v_lshlrev_b32_e32 v106, 16, v110
	v_and_b32_e32 v107, 0xffff0000, v110
	v_lshlrev_b32_e32 v108, 16, v111
	v_and_b32_e32 v109, 0xffff0000, v111
	v_lshlrev_b32_e32 v110, 16, v112
	v_and_b32_e32 v111, 0xffff0000, v112
	v_lshlrev_b32_e32 v100, 16, v101
	v_and_b32_e32 v101, 0xffff0000, v101
	v_lshlrev_b32_e32 v138, 16, v104
	v_and_b32_e32 v139, 0xffff0000, v104
	v_lshlrev_b32_e32 v140, 16, v105
	v_and_b32_e32 v141, 0xffff0000, v105
	s_waitcnt lgkmcnt(0)
	v_pk_mul_f32 v[104:105], v[188:189], v[132:133]
	v_lshlrev_b32_e32 v112, 16, v113
	v_and_b32_e32 v113, 0xffff0000, v113
	v_pk_mul_f32 v[110:111], v[188:189], v[110:111]
	v_add_f32_e32 v24, v163, v165
	v_pk_mul_f32 v[100:101], v[190:191], v[100:101]
	v_pk_mul_f32 v[112:113], v[190:191], v[112:113]
	v_add_f32_e32 v25, v164, v166
	ds_bpermute_b32 v26, v91, v24
	ds_bpermute_b32 v27, v91, v25
	v_lshlrev_b32_e32 v130, 16, v98
	v_and_b32_e32 v131, 0xffff0000, v98
	v_lshlrev_b32_e32 v98, 16, v99
	s_waitcnt lgkmcnt(1)
	v_add_f32_e32 v24, v24, v26
	s_waitcnt lgkmcnt(0)
	v_add_f32_e32 v25, v25, v27
	ds_bpermute_b32 v26, v92, v24
	ds_bpermute_b32 v27, v92, v25
	v_and_b32_e32 v99, 0xffff0000, v99
	v_lshlrev_b32_e32 v134, 16, v102
	v_and_b32_e32 v135, 0xffff0000, v102
	s_waitcnt lgkmcnt(1)
	v_add_f32_e32 v24, v24, v26
	s_waitcnt lgkmcnt(0)
	v_add_f32_e32 v25, v25, v27
	ds_bpermute_b32 v26, v93, v24
	ds_bpermute_b32 v27, v93, v25
	v_lshlrev_b32_e32 v136, 16, v103
	v_and_b32_e32 v137, 0xffff0000, v103
	v_pk_mul_f32 v[102:103], v[184:185], v[130:131]
	s_waitcnt lgkmcnt(1)
	v_add_f32_e32 v24, v24, v26
	s_waitcnt lgkmcnt(0)
	v_add_f32_e32 v25, v25, v27
	ds_bpermute_b32 v26, v94, v24
	ds_bpermute_b32 v27, v94, v25
	v_pk_mul_f32 v[106:107], v[184:185], v[106:107]
	v_pk_mul_f32 v[98:99], v[186:187], v[98:99]
	v_pk_mul_f32 v[108:109], v[186:187], v[108:109]
	s_waitcnt lgkmcnt(1)
	v_add_f32_e32 v24, v24, v26
	s_waitcnt lgkmcnt(0)
	v_add_f32_e32 v25, v25, v27
	ds_bpermute_b32 v26, v95, v24
	ds_bpermute_b32 v27, v95, v25
	v_lshlrev_b32_e32 v130, 16, v114
	v_and_b32_e32 v131, 0xffff0000, v114
	v_lshlrev_b32_e32 v114, 16, v115
	s_waitcnt lgkmcnt(1)
	v_add_f32_e32 v24, v24, v26
	s_waitcnt lgkmcnt(0)
	v_add_f32_e32 v25, v25, v27
	v_fmamk_f32 v24, v24, 0x39800000, v96
	v_fmamk_f32 v25, v25, 0x39800000, v96
	v_mul_f32_e32 v26, 0x4f800000, v24
	v_cmp_gt_f32_e64 s[0:1], s18, v24
	v_mul_f32_e32 v27, 0x4f800000, v25
	v_cmp_gt_f32_e32 vcc, s18, v25
	v_cndmask_b32_e64 v24, v24, v26, s[0:1]
	v_sqrt_f32_e32 v26, v24
	v_cndmask_b32_e32 v25, v25, v27, vcc
	v_sqrt_f32_e32 v27, v25
	v_and_b32_e32 v115, 0xffff0000, v115
	v_add_u32_e32 v28, -1, v26
	v_add_u32_e32 v29, 1, v26
	v_add_u32_e32 v30, -1, v27
	v_fma_f32 v163, -v28, v26, v24
	v_add_u32_e32 v31, 1, v27
	v_fma_f32 v164, -v29, v26, v24
	v_fma_f32 v165, -v30, v27, v25
	v_cmp_ge_f32_e64 s[2:3], 0, v163
	v_fma_f32 v166, -v31, v27, v25
	v_cmp_lt_f32_e64 s[4:5], 0, v164
	v_cndmask_b32_e64 v26, v26, v28, s[2:3]
	v_cmp_ge_f32_e64 s[2:3], 0, v165
	v_cndmask_b32_e64 v26, v26, v29, s[4:5]
	v_mul_f32_e32 v28, 0x37800000, v26
	v_cndmask_b32_e64 v27, v27, v30, s[2:3]
	v_cmp_lt_f32_e64 s[2:3], 0, v166
	v_cndmask_b32_e64 v26, v26, v28, s[0:1]
	v_cmp_class_f32_e64 s[0:1], v24, v97
	v_cndmask_b32_e64 v27, v27, v31, s[2:3]
	v_mul_f32_e32 v29, 0x37800000, v27
	v_cndmask_b32_e32 v27, v27, v29, vcc
	v_cmp_class_f32_e32 vcc, v25, v97
	v_cndmask_b32_e64 v24, v26, v24, s[0:1]
	v_div_scale_f32 v26, s[0:1], v24, v24, 1.0
	v_cndmask_b32_e32 v25, v27, v25, vcc
	v_div_scale_f32 v28, s[0:1], v25, v25, 1.0
	v_rcp_f32_e32 v30, v26
	v_rcp_f32_e32 v31, v28
	v_div_scale_f32 v27, vcc, 1.0, v24, 1.0
	v_fma_f32 v163, -v26, v30, 1.0
	v_fma_f32 v164, -v28, v31, 1.0
	v_fmac_f32_e32 v30, v163, v30
	v_div_scale_f32 v29, s[0:1], 1.0, v25, 1.0
	v_fmac_f32_e32 v31, v164, v31
	v_mul_f32_e32 v163, v27, v30
	v_mul_f32_e32 v164, v29, v31
	v_fma_f32 v165, -v26, v163, v27
	v_fma_f32 v166, -v28, v164, v29
	v_fmac_f32_e32 v163, v165, v30
	v_fmac_f32_e32 v164, v166, v31
	v_fma_f32 v26, -v26, v163, v27
	v_fma_f32 v27, -v28, v164, v29
	v_div_fmas_f32 v26, v26, v30, v163
	s_mov_b64 vcc, s[0:1]
	v_div_fixup_f32 v26, v26, v24, 1.0
	v_div_fmas_f32 v24, v27, v31, v164
	v_div_fixup_f32 v24, v24, v25, 1.0
	v_pk_mul_f32 v[28:29], v[26:27], v[102:103] op_sel_hi:[0,1]
	v_pk_mul_f32 v[30:31], v[26:27], v[98:99] op_sel_hi:[0,1]
	v_pk_mul_f32 v[98:99], v[26:27], v[104:105] op_sel_hi:[0,1]
	v_pk_mul_f32 v[100:101], v[26:27], v[100:101] op_sel_hi:[0,1]
	v_pk_mul_f32 v[102:103], v[24:25], v[106:107] op_sel_hi:[0,1]
	v_pk_mul_f32 v[104:105], v[24:25], v[108:109] op_sel_hi:[0,1]
	v_pk_mul_f32 v[106:107], v[24:25], v[110:111] op_sel_hi:[0,1]
	v_pk_mul_f32 v[108:109], v[24:25], v[112:113] op_sel_hi:[0,1]
	global_store_dwordx4 v[78:79], v[28:31], off nt
	global_store_dwordx4 v[78:79], v[98:101], off offset:16 nt
	global_store_dwordx4 v[76:77], v[102:105], off nt
	global_store_dwordx4 v[76:77], v[106:109], off offset:16 nt
	s_nop 1
	v_lshlrev_b32_e32 v132, 16, v116
	v_and_b32_e32 v133, 0xffff0000, v116
	v_lshlrev_b32_e32 v116, 16, v117
	v_and_b32_e32 v117, 0xffff0000, v117
	v_lshlrev_b32_e32 v148, 16, v118
	v_and_b32_e32 v149, 0xffff0000, v118
	v_lshlrev_b32_e32 v118, 16, v119
	v_and_b32_e32 v119, 0xffff0000, v119
	v_lshlrev_b32_e32 v150, 16, v120
; __device__ __forceinline__ float bflo(unsigned w) { return __uint_as_float(w << 16); }
; __device__ __forceinline__ float bfhi(unsigned w) { return __uint_as_float(w & 0xffff0000u); }
; __global__ void __launch_bounds__(NWAVES * 64, 2) fwd(Args args) {
;     ...
;             for (int j = 0; j < 8; ++j) { const f32x4 g0 = gfp[128 * j], g1 = gfp[128 * j + 1]; const u32x4 w = wa[j], w2 = wb[j];
;                 const f32x4 v0 = {bflo(w.x) * g0[0] * rsa, bfhi(w.x) * g0[1] * rsa, bflo(w.y) * g0[2] * rsa, bfhi(w.y) * g0[3] * rsa}, v1 = {bflo(w.z) * g1[0] * rsa, bfhi(w.z) * g1[1] * rsa, bflo(w.w) * g1[2] * rsa, bfhi(w.w) * g1[3] * rsa};
;                 const f32x4 u0 = {bflo(w2.x) * g0[0] * rsb, bfhi(w2.x) * g0[1] * rsb, bflo(w2.y) * g0[2] * rsb, bfhi(w2.y) * g0[3] * rsb}, u1 = {bflo(w2.z) * g1[0] * rsb, bfhi(w2.z) * g1[1] * rsb, bflo(w2.w) * g1[2] * rsb, bfhi(w2.w) * g1[3] * rsb};
;                 __builtin_nontemporal_store(v0, oa + 128 * j); __builtin_nontemporal_store(v1, oa + 128 * j + 1); __builtin_nontemporal_store(u0, ob + 128 * j); __builtin_nontemporal_store(u1, ob + 128 * j + 1); } }
	v_and_b32_e32 v151, 0xffff0000, v120
	v_lshlrev_b32_e32 v120, 16, v121
	v_and_b32_e32 v121, 0xffff0000, v121
	v_lshlrev_b32_e32 v152, 16, v122
	v_and_b32_e32 v153, 0xffff0000, v122
	v_lshlrev_b32_e32 v122, 16, v123
	v_and_b32_e32 v123, 0xffff0000, v123
	v_lshlrev_b32_e32 v154, 16, v124
	v_and_b32_e32 v155, 0xffff0000, v124
	v_lshlrev_b32_e32 v124, 16, v125
	v_and_b32_e32 v125, 0xffff0000, v125
	v_lshlrev_b32_e32 v156, 16, v126
	v_and_b32_e32 v157, 0xffff0000, v126
	v_lshlrev_b32_e32 v126, 16, v127
	v_and_b32_e32 v127, 0xffff0000, v127
	v_lshlrev_b32_e32 v158, 16, v128
	v_and_b32_e32 v159, 0xffff0000, v128
	v_lshlrev_b32_e32 v128, 16, v129
	v_and_b32_e32 v129, 0xffff0000, v129
	v_lshlrev_b32_e32 v160, 16, v36
	v_and_b32_e32 v161, 0xffff0000, v36
	v_lshlrev_b32_e32 v36, 16, v37
	v_and_b32_e32 v37, 0xffff0000, v37
	v_lshlrev_b32_e32 v162, 16, v38
	v_and_b32_e32 v163, 0xffff0000, v38
	v_lshlrev_b32_e32 v38, 16, v39
	v_and_b32_e32 v39, 0xffff0000, v39
	v_pk_mul_f32 v[102:103], v[192:193], v[134:135]
	v_pk_mul_f32 v[104:105], v[194:195], v[136:137]
	v_pk_mul_f32 v[106:107], v[196:197], v[138:139]
	v_pk_mul_f32 v[108:109], v[198:199], v[140:141]
	v_pk_mul_f32 v[110:111], v[192:193], v[130:131]
	v_pk_mul_f32 v[112:113], v[194:195], v[114:115]
	v_pk_mul_f32 v[114:115], v[196:197], v[132:133]
	v_pk_mul_f32 v[116:117], v[198:199], v[116:117]
	v_pk_mul_f32 v[28:29], v[26:27], v[102:103] op_sel_hi:[0,1]
	v_pk_mul_f32 v[30:31], v[26:27], v[104:105] op_sel_hi:[0,1]
	v_pk_mul_f32 v[98:99], v[26:27], v[106:107] op_sel_hi:[0,1]
	v_pk_mul_f32 v[100:101], v[26:27], v[108:109] op_sel_hi:[0,1]
	v_pk_mul_f32 v[102:103], v[24:25], v[110:111] op_sel_hi:[0,1]
	v_pk_mul_f32 v[104:105], v[24:25], v[112:113] op_sel_hi:[0,1]
	v_pk_mul_f32 v[106:107], v[24:25], v[114:115] op_sel_hi:[0,1]
	v_pk_mul_f32 v[108:109], v[24:25], v[116:117] op_sel_hi:[0,1]
	global_store_dwordx4 v[78:79], v[28:31], off offset:2048 nt
	global_store_dwordx4 v[78:79], v[98:101], off offset:2064 nt
	global_store_dwordx4 v[76:77], v[102:105], off offset:2048 nt
	global_store_dwordx4 v[76:77], v[106:109], off offset:2064 nt
	s_nop 1
	v_pk_mul_f32 v[88:89], v[200:201], v[88:89]
	v_pk_mul_f32 v[102:103], v[202:203], v[142:143]
	v_pk_mul_f32 v[104:105], v[204:205], v[144:145]
	v_pk_mul_f32 v[106:107], v[206:207], v[146:147]
	v_pk_mul_f32 v[108:109], v[200:201], v[148:149]
	v_pk_mul_f32 v[110:111], v[202:203], v[118:119]
	v_pk_mul_f32 v[112:113], v[204:205], v[150:151]
	v_pk_mul_f32 v[114:115], v[206:207], v[120:121]
	v_pk_mul_f32 v[28:29], v[26:27], v[88:89] op_sel_hi:[0,1]
	v_pk_mul_f32 v[30:31], v[26:27], v[102:103] op_sel_hi:[0,1]
	v_pk_mul_f32 v[98:99], v[26:27], v[104:105] op_sel_hi:[0,1]
	v_pk_mul_f32 v[100:101], v[26:27], v[106:107] op_sel_hi:[0,1]
	v_pk_mul_f32 v[102:103], v[24:25], v[108:109] op_sel_hi:[0,1]
	v_pk_mul_f32 v[104:105], v[24:25], v[110:111] op_sel_hi:[0,1]
	v_pk_mul_f32 v[106:107], v[24:25], v[112:113] op_sel_hi:[0,1]
	v_pk_mul_f32 v[108:109], v[24:25], v[114:115] op_sel_hi:[0,1]
	global_store_dwordx4 v[80:81], v[28:31], off offset:-4096 nt
	global_store_dwordx4 v[84:85], v[98:101], off offset:16 nt
	global_store_dwordx4 v[82:83], v[102:105], off offset:-4096 nt
	global_store_dwordx4 v[86:87], v[106:109], off offset:16 nt
	s_nop 1
	v_pk_mul_f32 v[88:89], v[208:209], v[152:153]
	v_pk_mul_f32 v[102:103], v[210:211], v[122:123]
	v_pk_mul_f32 v[104:105], v[212:213], v[154:155]
	v_pk_mul_f32 v[106:107], v[214:215], v[124:125]
	v_pk_mul_f32 v[108:109], v[208:209], v[156:157]
	v_pk_mul_f32 v[110:111], v[210:211], v[126:127]
	v_pk_mul_f32 v[112:113], v[212:213], v[158:159]
	v_pk_mul_f32 v[114:115], v[214:215], v[128:129]
	v_pk_mul_f32 v[28:29], v[26:27], v[88:89] op_sel_hi:[0,1]
	v_pk_mul_f32 v[30:31], v[26:27], v[102:103] op_sel_hi:[0,1]
	v_pk_mul_f32 v[98:99], v[26:27], v[104:105] op_sel_hi:[0,1]
	v_pk_mul_f32 v[100:101], v[26:27], v[106:107] op_sel_hi:[0,1]
	v_pk_mul_f32 v[102:103], v[24:25], v[108:109] op_sel_hi:[0,1]
	v_pk_mul_f32 v[104:105], v[24:25], v[110:111] op_sel_hi:[0,1]
	v_pk_mul_f32 v[106:107], v[24:25], v[112:113] op_sel_hi:[0,1]
	v_pk_mul_f32 v[108:109], v[24:25], v[114:115] op_sel_hi:[0,1]
	global_store_dwordx4 v[84:85], v[28:31], off offset:2048 nt
	global_store_dwordx4 v[84:85], v[98:101], off offset:2064 nt
	global_store_dwordx4 v[86:87], v[102:105], off offset:2048 nt
	global_store_dwordx4 v[86:87], v[106:109], off offset:2064 nt
	s_nop 1
	v_lshlrev_b32_e32 v88, 16, v32
	v_and_b32_e32 v89, 0xffff0000, v32
	v_lshlrev_b32_e32 v32, 16, v33
	v_and_b32_e32 v33, 0xffff0000, v33
	v_lshlrev_b32_e32 v98, 16, v34
	v_and_b32_e32 v99, 0xffff0000, v34
	v_lshlrev_b32_e32 v34, 16, v35
	v_and_b32_e32 v35, 0xffff0000, v35
	v_pk_mul_f32 v[100:101], v[216:217], v[160:161]
	v_pk_mul_f32 v[36:37], v[218:219], v[36:37]
	v_pk_mul_f32 v[102:103], v[220:221], v[162:163]
	v_pk_mul_f32 v[38:39], v[222:223], v[38:39]
	v_pk_mul_f32 v[88:89], v[216:217], v[88:89]
	v_pk_mul_f32 v[104:105], v[218:219], v[32:33]
	v_pk_mul_f32 v[84:85], v[220:221], v[98:99]
	v_pk_mul_f32 v[86:87], v[222:223], v[34:35]
	v_pk_mul_f32 v[28:29], v[26:27], v[100:101] op_sel_hi:[0,1]
	v_pk_mul_f32 v[30:31], v[26:27], v[36:37] op_sel_hi:[0,1]
	v_pk_mul_f32 v[32:33], v[26:27], v[102:103] op_sel_hi:[0,1]
	v_pk_mul_f32 v[34:35], v[26:27], v[38:39] op_sel_hi:[0,1]
	v_pk_mul_f32 v[36:37], v[24:25], v[88:89] op_sel_hi:[0,1]
; __device__ __forceinline__ float bflo(unsigned w) { return __uint_as_float(w << 16); }
; __device__ __forceinline__ float bfhi(unsigned w) { return __uint_as_float(w & 0xffff0000u); }
; __global__ void __launch_bounds__(NWAVES * 64, 2) fwd(Args args) {
;     ...
;             for (int j = 0; j < 8; ++j) { const f32x4 g0 = gfp[128 * j], g1 = gfp[128 * j + 1]; const u32x4 w = wa[j], w2 = wb[j];
;                 const f32x4 v0 = {bflo(w.x) * g0[0] * rsa, bfhi(w.x) * g0[1] * rsa, bflo(w.y) * g0[2] * rsa, bfhi(w.y) * g0[3] * rsa}, v1 = {bflo(w.z) * g1[0] * rsa, bfhi(w.z) * g1[1] * rsa, bflo(w.w) * g1[2] * rsa, bfhi(w.w) * g1[3] * rsa};
;                 const f32x4 u0 = {bflo(w2.x) * g0[0] * rsb, bfhi(w2.x) * g0[1] * rsb, bflo(w2.y) * g0[2] * rsb, bfhi(w2.y) * g0[3] * rsb}, u1 = {bflo(w2.z) * g1[0] * rsb, bfhi(w2.z) * g1[1] * rsb, bflo(w2.w) * g1[2] * rsb, bfhi(w2.w) * g1[3] * rsb};
;                 __builtin_nontemporal_store(v0, oa + 128 * j); __builtin_nontemporal_store(v1, oa + 128 * j + 1); __builtin_nontemporal_store(u0, ob + 128 * j); __builtin_nontemporal_store(u1, ob + 128 * j + 1); } }
	v_pk_mul_f32 v[38:39], v[24:25], v[104:105] op_sel_hi:[0,1]
	v_pk_mul_f32 v[84:85], v[24:25], v[84:85] op_sel_hi:[0,1]
	v_pk_mul_f32 v[86:87], v[24:25], v[86:87] op_sel_hi:[0,1]
	global_store_dwordx4 v[80:81], v[28:31], off nt
	global_store_dwordx4 v[80:81], v[32:35], off offset:16 nt
	global_store_dwordx4 v[82:83], v[36:39], off nt
	global_store_dwordx4 v[82:83], v[84:87], off offset:16 nt
	s_nop 1
	v_lshlrev_b32_e32 v36, 16, v20
	v_and_b32_e32 v37, 0xffff0000, v20
	v_lshlrev_b32_e32 v20, 16, v21
	v_and_b32_e32 v21, 0xffff0000, v21
	v_lshlrev_b32_e32 v38, 16, v22
	v_and_b32_e32 v39, 0xffff0000, v22
	v_lshlrev_b32_e32 v22, 16, v23
	v_and_b32_e32 v23, 0xffff0000, v23
	v_lshlrev_b32_e32 v84, 16, v16
	v_and_b32_e32 v85, 0xffff0000, v16
	v_lshlrev_b32_e32 v16, 16, v17
	v_and_b32_e32 v17, 0xffff0000, v17
	v_lshlrev_b32_e32 v86, 16, v18
	v_and_b32_e32 v87, 0xffff0000, v18
	v_lshlrev_b32_e32 v18, 16, v19
	v_and_b32_e32 v19, 0xffff0000, v19
	v_pk_mul_f32 v[36:37], v[224:225], v[36:37]
	v_pk_mul_f32 v[20:21], v[226:227], v[20:21]
	v_pk_mul_f32 v[38:39], v[228:229], v[38:39]
	v_pk_mul_f32 v[22:23], v[230:231], v[22:23]
	v_pk_mul_f32 v[28:29], v[224:225], v[84:85]
	v_pk_mul_f32 v[30:31], v[226:227], v[16:17]
	v_pk_mul_f32 v[32:33], v[228:229], v[86:87]
	v_pk_mul_f32 v[34:35], v[230:231], v[18:19]
	v_pk_mul_f32 v[16:17], v[26:27], v[36:37] op_sel_hi:[0,1]
	v_pk_mul_f32 v[18:19], v[26:27], v[20:21] op_sel_hi:[0,1]
	v_pk_mul_f32 v[20:21], v[26:27], v[38:39] op_sel_hi:[0,1]
	v_pk_mul_f32 v[22:23], v[26:27], v[22:23] op_sel_hi:[0,1]
	v_pk_mul_f32 v[28:29], v[24:25], v[28:29] op_sel_hi:[0,1]
	v_pk_mul_f32 v[30:31], v[24:25], v[30:31] op_sel_hi:[0,1]
	v_pk_mul_f32 v[32:33], v[24:25], v[32:33] op_sel_hi:[0,1]
	v_pk_mul_f32 v[34:35], v[24:25], v[34:35] op_sel_hi:[0,1]
	global_store_dwordx4 v[80:81], v[16:19], off offset:2048 nt
	global_store_dwordx4 v[80:81], v[20:23], off offset:2064 nt
	global_store_dwordx4 v[82:83], v[28:31], off offset:2048 nt
	global_store_dwordx4 v[82:83], v[32:35], off offset:2064 nt
	s_nop 1
	v_add_co_u32_e32 v28, vcc, s21, v78
	v_lshlrev_b32_e32 v32, 16, v12
	v_and_b32_e32 v33, 0xffff0000, v12
	v_lshlrev_b32_e32 v12, 16, v13
	v_and_b32_e32 v13, 0xffff0000, v13
	v_addc_co_u32_e32 v29, vcc, 0, v79, vcc
	v_lshlrev_b32_e32 v34, 16, v14
	v_and_b32_e32 v35, 0xffff0000, v14
	v_lshlrev_b32_e32 v14, 16, v15
	v_and_b32_e32 v15, 0xffff0000, v15
	v_lshlrev_b32_e32 v36, 16, v8
	v_and_b32_e32 v37, 0xffff0000, v8
	v_lshlrev_b32_e32 v8, 16, v9
	v_and_b32_e32 v9, 0xffff0000, v9
	v_lshlrev_b32_e32 v38, 16, v10
	v_and_b32_e32 v39, 0xffff0000, v10
	v_lshlrev_b32_e32 v10, 16, v11
	v_and_b32_e32 v11, 0xffff0000, v11
	v_add_co_u32_e32 v30, vcc, s21, v76
	v_pk_mul_f32 v[32:33], v[232:233], v[32:33]
	v_pk_mul_f32 v[12:13], v[234:235], v[12:13]
	v_pk_mul_f32 v[34:35], v[236:237], v[34:35]
	v_pk_mul_f32 v[14:15], v[238:239], v[14:15]
	v_pk_mul_f32 v[16:17], v[232:233], v[36:37]
	v_pk_mul_f32 v[18:19], v[234:235], v[8:9]
	v_pk_mul_f32 v[20:21], v[236:237], v[38:39]
	v_pk_mul_f32 v[22:23], v[238:239], v[10:11]
	v_pk_mul_f32 v[8:9], v[26:27], v[32:33] op_sel_hi:[0,1]
	v_pk_mul_f32 v[10:11], v[26:27], v[12:13] op_sel_hi:[0,1]
	v_addc_co_u32_e32 v31, vcc, 0, v77, vcc
	v_pk_mul_f32 v[12:13], v[26:27], v[34:35] op_sel_hi:[0,1]
	v_pk_mul_f32 v[14:15], v[26:27], v[14:15] op_sel_hi:[0,1]
	v_pk_mul_f32 v[16:17], v[24:25], v[16:17] op_sel_hi:[0,1]
	v_pk_mul_f32 v[18:19], v[24:25], v[18:19] op_sel_hi:[0,1]
	v_pk_mul_f32 v[20:21], v[24:25], v[20:21] op_sel_hi:[0,1]
	v_pk_mul_f32 v[22:23], v[24:25], v[22:23] op_sel_hi:[0,1]
	global_store_dwordx4 v[28:29], v[8:11], off nt
	global_store_dwordx4 v[28:29], v[12:15], off offset:16 nt
	global_store_dwordx4 v[30:31], v[16:19], off nt
	global_store_dwordx4 v[30:31], v[20:23], off offset:16 nt
	s_nop 1
	v_lshlrev_b32_e32 v16, 16, v4
	v_and_b32_e32 v17, 0xffff0000, v4
	v_lshlrev_b32_e32 v4, 16, v5
	v_and_b32_e32 v5, 0xffff0000, v5
	v_lshlrev_b32_e32 v18, 16, v6
	v_and_b32_e32 v19, 0xffff0000, v6
	v_lshlrev_b32_e32 v6, 16, v7
	v_and_b32_e32 v7, 0xffff0000, v7
	v_lshlrev_b32_e32 v20, 16, v0
	v_and_b32_e32 v21, 0xffff0000, v0
	v_lshlrev_b32_e32 v0, 16, v1
	v_and_b32_e32 v1, 0xffff0000, v1
	v_lshlrev_b32_e32 v22, 16, v2
	v_and_b32_e32 v23, 0xffff0000, v2
	v_lshlrev_b32_e32 v2, 16, v3
	v_and_b32_e32 v3, 0xffff0000, v3
	v_pk_mul_f32 v[16:17], v[240:241], v[16:17]
	v_pk_mul_f32 v[4:5], v[242:243], v[4:5]
	v_pk_mul_f32 v[18:19], v[244:245], v[18:19]
	v_pk_mul_f32 v[6:7], v[246:247], v[6:7]
	v_pk_mul_f32 v[8:9], v[240:241], v[20:21]
	v_pk_mul_f32 v[10:11], v[242:243], v[0:1]
	v_pk_mul_f32 v[12:13], v[244:245], v[22:23]
	v_pk_mul_f32 v[14:15], v[246:247], v[2:3]
	v_pk_mul_f32 v[0:1], v[26:27], v[16:17] op_sel_hi:[0,1]
	v_pk_mul_f32 v[2:3], v[26:27], v[4:5] op_sel_hi:[0,1]
	v_pk_mul_f32 v[4:5], v[26:27], v[18:19] op_sel_hi:[0,1]
	v_pk_mul_f32 v[6:7], v[26:27], v[6:7] op_sel_hi:[0,1]
	v_pk_mul_f32 v[8:9], v[24:25], v[8:9] op_sel_hi:[0,1]
	v_pk_mul_f32 v[10:11], v[24:25], v[10:11] op_sel_hi:[0,1]
	v_pk_mul_f32 v[12:13], v[24:25], v[12:13] op_sel_hi:[0,1]
	v_pk_mul_f32 v[14:15], v[24:25], v[14:15] op_sel_hi:[0,1]
	global_store_dwordx4 v[28:29], v[0:3], off offset:2048 nt
	global_store_dwordx4 v[28:29], v[4:7], off offset:2064 nt
	global_store_dwordx4 v[30:31], v[8:11], off offset:2048 nt
	global_store_dwordx4 v[30:31], v[12:15], off offset:2064 nt
	s_cbranch_scc1 .LBB0_1714
